# final norm gains preloaded
# baseline (speedup 1.0000x reference)
.LBB0_909:
	s_lshl_b32 s6, s2, 3
	v_lshlrev_b32_e32 v1, 2, v0
	v_ashrrev_i32_e32 v21, 31, v20
	v_and_b32_e32 v0, 63, v0
	v_and_b32_e32 v2, 0xfc, v1
	v_lshlrev_b64 v[22:23], 13, v[20:21]
	v_lshlrev_b32_e32 v0, 4, v0
	s_movk_i32 s2, 0x1c00
	s_ashr_i32 s7, s6, 31
	v_or3_b32 v22, v22, v0, s2
	s_lshl_b64 s[8:9], s[6:7], 13
	s_mov_b64 s[10:11], 0
	v_lshlrev_b32_e32 v168, 2, v2
	s_load_dwordx2 s[12:13], s[0:1], 0x140
	s_waitcnt lgkmcnt(0)
	global_load_dwordx4 v[72:75], v168, s[12:13]
	global_load_dwordx4 v[76:79], v168, s[12:13] offset:1024
	global_load_dwordx4 v[80:83], v168, s[12:13] offset:2048
	global_load_dwordx4 v[84:87], v168, s[12:13] offset:3072
	s_add_u32 s12, s12, 0x1000
	s_addc_u32 s13, s13, 0
	global_load_dwordx4 v[88:91], v168, s[12:13]
	global_load_dwordx4 v[92:95], v168, s[12:13] offset:1024
	global_load_dwordx4 v[96:99], v168, s[12:13] offset:2048
	global_load_dwordx4 v[100:103], v168, s[12:13] offset:3072
.LBB0_910:
	s_load_dwordx2 s[12:13], s[0:1], 0x148
	v_add_u32_e32 v20, s6, v20
	s_waitcnt lgkmcnt(0)
	v_lshl_add_u64 v[24:25], s[12:13], 0, v[22:23]
	v_add_co_u32_e32 v26, vcc, 0xfffff000, v24
	global_load_dwordx4 v[8:11], v[24:25], off offset:-3072
	global_load_dwordx4 v[16:19], v[24:25], off offset:-4096
	global_load_dwordx4 v[12:15], v[24:25], off offset:-2048
	global_load_dwordx4 v[4:7], v[24:25], off offset:-1024
	v_addc_co_u32_e32 v27, vcc, -1, v25, vcc
	global_load_dwordx4 v[28:31], v[26:27], off offset:-3072
	global_load_dwordx4 v[32:35], v[26:27], off offset:-2048
	global_load_dwordx4 v[36:39], v[26:27], off offset:-1024
	global_load_dwordx4 v[0:3], v[24:25], off
	s_load_dwordx2 s[12:13], s[0:1], 0x140
	v_lshl_add_u64 v[22:23], v[22:23], 0, s[8:9]
	s_waitcnt lgkmcnt(0)
	s_waitcnt vmcnt(0)
	s_nop 1
	v_mov_b64_e32 v[40:41], v[72:73]
	v_mov_b64_e32 v[42:43], v[74:75]
	v_mul_f32_e32 v60, v10, v10
	v_mul_f32_e32 v44, v17, v17
	v_pk_mul_f32 v[48:49], v[14:15], v[14:15]
	v_pk_mul_f32 v[50:51], v[12:13], v[12:13]
	v_pk_fma_f32 v[44:45], v[16:17], v[16:17], v[44:45] op_sel_hi:[1,1,0]
	v_pk_mov_b32 v[56:57], v[50:51], v[48:49] op_sel:[1,0]
	v_mov_b32_e32 v51, v49
	v_pk_mul_f32 v[58:59], v[38:39], v[38:39]
	v_mov_b32_e32 v45, v60
	v_pk_mul_f32 v[60:61], v[36:37], v[36:37]
	v_mul_f32_e32 v46, v19, v19
	v_mul_f32_e32 v52, v5, v5
	v_mul_f32_e32 v54, v7, v7
	v_pk_add_f32 v[50:51], v[56:57], v[50:51]
	v_pk_mov_b32 v[56:57], v[60:61], v[58:59] op_sel:[1,0]
	v_mov_b32_e32 v61, v59
	v_mov_b32_e32 v58, v29
	v_mov_b32_e32 v59, v33
	v_mul_f32_e32 v63, v11, v11
	v_pk_fma_f32 v[46:47], v[18:19], v[18:19], v[46:47] op_sel_hi:[1,1,0]
	v_pk_fma_f32 v[48:49], v[4:5], v[4:5], v[52:53] op_sel_hi:[1,1,0]
	v_pk_fma_f32 v[52:53], v[6:7], v[6:7], v[54:55] op_sel_hi:[1,1,0]
	v_mov_b32_e32 v54, v28
	v_mov_b32_e32 v55, v32
	v_pk_mul_f32 v[58:59], v[58:59], v[58:59]
	v_mov_b32_e32 v47, v63
	v_pk_fma_f32 v[54:55], v[54:55], v[54:55], v[58:59]
	v_mov_b32_e32 v58, v31
	v_mov_b32_e32 v59, v35
	v_pk_add_f32 v[44:45], v[44:45], v[46:47]
	v_mov_b32_e32 v46, v30
	v_mov_b32_e32 v47, v34
	v_pk_mul_f32 v[58:59], v[58:59], v[58:59]
	v_mul_f32_e32 v49, v2, v2
	v_pk_fma_f32 v[46:47], v[46:47], v[46:47], v[58:59]
	v_mul_f32_e32 v53, v3, v3
	v_pk_add_f32 v[56:57], v[56:57], v[60:61]
	v_pk_add_f32 v[46:47], v[54:55], v[46:47]
	v_mul_f32_e32 v21, v8, v8
	v_mul_f32_e32 v62, v9, v9
	v_pk_add_f32 v[48:49], v[48:49], v[52:53]
	v_pk_add_f32 v[52:53], v[56:57], v[56:57] op_sel:[0,1] op_sel_hi:[1,0]
	v_pk_add_f32 v[46:47], v[46:47], v[46:47] op_sel:[0,1] op_sel_hi:[1,0]
	v_mov_b32_e32 v53, v62
	v_mov_b32_e32 v47, v21
	v_pk_add_f32 v[46:47], v[46:47], v[52:53]
	v_mul_f32_e32 v63, v0, v0
	v_pk_add_f32 v[44:45], v[46:47], v[44:45]
	v_mul_f32_e32 v58, v1, v1
	v_pk_add_f32 v[50:51], v[50:51], v[50:51] op_sel:[0,1] op_sel_hi:[1,0]
	v_pk_add_f32 v[44:45], v[44:45], v[44:45] op_sel:[0,1] op_sel_hi:[1,0]
	v_mov_b32_e32 v51, v58
	v_mov_b32_e32 v45, v63
	v_pk_add_f32 v[44:45], v[44:45], v[50:51]
	s_nop 0
	v_pk_add_f32 v[44:45], v[44:45], v[48:49]
	s_nop 0
	v_add_f32_e32 v21, v44, v45
	s_nop 1
	v_add_f32_dpp v21, v21, v21 quad_perm:[1,0,3,2] row_mask:0xf bank_mask:0xf bound_ctrl:1
	s_nop 1
	v_add_f32_dpp v21, v21, v21 quad_perm:[2,3,0,1] row_mask:0xf bank_mask:0xf bound_ctrl:1
	s_nop 1
	v_add_f32_dpp v21, v21, v21 row_half_mirror row_mask:0xf bank_mask:0xf bound_ctrl:1
	s_nop 1
	v_add_f32_dpp v21, v21, v21 row_mirror row_mask:0xf bank_mask:0xf bound_ctrl:1
	s_nop 0
	v_readlane_b32 s2, v21, 16
	v_readlane_b32 s7, v21, 48
	v_readlane_b32 s12, v21, 0
	v_readlane_b32 s13, v21, 32
	v_mov_b32_e32 v44, s2
	v_mov_b32_e32 v45, s7
	v_pk_add_f32 v[44:45], s[12:13], v[44:45]
	s_nop 0
	v_add_f32_e32 v21, v44, v45
	v_fmamk_f32 v21, v21, 0x3a000000, v227
	v_mul_f32_e32 v44, 0x4b800000, v21
	v_cmp_gt_f32_e32 vcc, s29, v21
	s_nop 1
	v_cndmask_b32_e32 v21, v21, v44, vcc
	v_rsq_f32_e32 v21, v21
	s_nop 0
	v_mul_f32_e32 v44, 0x45800000, v21
	v_cndmask_b32_e32 v44, v21, v44, vcc
	v_pk_mul_f32 v[28:29], v[44:45], v[28:29] op_sel_hi:[0,1]
	v_pk_mul_f32 v[30:31], v[44:45], v[30:31] op_sel_hi:[0,1]
	v_pk_mul_f32 v[30:31], v[30:31], v[42:43]
	v_pk_mul_f32 v[28:29], v[28:29], v[40:41]
	global_store_dwordx4 v[26:27], v[28:31], off offset:-3072
	s_load_dwordx2 s[12:13], s[0:1], 0x140
	v_pk_mul_f32 v[34:35], v[44:45], v[34:35] op_sel_hi:[0,1]
	v_pk_mul_f32 v[32:33], v[44:45], v[32:33] op_sel_hi:[0,1]
	v_pk_mul_f32 v[18:19], v[44:45], v[18:19] op_sel_hi:[0,1]
	v_pk_mul_f32 v[16:17], v[44:45], v[16:17] op_sel_hi:[0,1]
	s_waitcnt lgkmcnt(0)
	s_nop 1
	v_mov_b64_e32 v[28:29], v[76:77]
	v_mov_b64_e32 v[30:31], v[78:79]
	v_pk_mul_f32 v[10:11], v[44:45], v[10:11] op_sel_hi:[0,1]
	v_pk_mul_f32 v[8:9], v[44:45], v[8:9] op_sel_hi:[0,1]
	v_pk_mul_f32 v[14:15], v[44:45], v[14:15] op_sel_hi:[0,1]
	v_pk_mul_f32 v[12:13], v[44:45], v[12:13] op_sel_hi:[0,1]
	v_pk_mul_f32 v[6:7], v[44:45], v[6:7] op_sel_hi:[0,1]
	v_pk_mul_f32 v[4:5], v[44:45], v[4:5] op_sel_hi:[0,1]
	v_pk_mul_f32 v[2:3], v[44:45], v[2:3] op_sel_hi:[0,1]
	v_pk_mul_f32 v[0:1], v[44:45], v[0:1] op_sel_hi:[0,1]
	v_pk_mul_f32 v[28:29], v[32:33], v[28:29]
	v_pk_mul_f32 v[30:31], v[34:35], v[30:31]
	global_store_dwordx4 v[26:27], v[28:31], off offset:-2048
	s_load_dwordx2 s[12:13], s[0:1], 0x140
	v_pk_mul_f32 v[32:33], v[44:45], v[38:39] op_sel_hi:[0,1]
	v_pk_mul_f32 v[34:35], v[44:45], v[36:37] op_sel_hi:[0,1]
	s_waitcnt lgkmcnt(0)
	s_nop 1
	v_mov_b64_e32 v[28:29], v[80:81]
	v_mov_b64_e32 v[30:31], v[82:83]
	v_pk_mul_f32 v[28:29], v[34:35], v[28:29]
	v_pk_mul_f32 v[30:31], v[32:33], v[30:31]
	global_store_dwordx4 v[26:27], v[28:31], off offset:-1024
	s_load_dwordx2 s[12:13], s[0:1], 0x140
	s_waitcnt lgkmcnt(0)
	s_nop 1
	v_mov_b64_e32 v[26:27], v[84:85]
	v_mov_b64_e32 v[28:29], v[86:87]
	v_pk_mul_f32 v[16:17], v[16:17], v[26:27]
	v_pk_mul_f32 v[18:19], v[18:19], v[28:29]
	global_store_dwordx4 v[24:25], v[16:19], off offset:-4096
	s_load_dwordx2 s[12:13], s[0:1], 0x140
	s_waitcnt lgkmcnt(0)
	v_lshl_add_u64 v[16:17], s[12:13], 0, v[168:169]
	v_add_co_u32_e32 v16, vcc, s3, v16
	s_nop 1
	v_addc_co_u32_e32 v17, vcc, 0, v17, vcc
	s_nop 1
	v_mov_b64_e32 v[16:17], v[88:89]
	v_mov_b64_e32 v[18:19], v[90:91]
	v_pk_mul_f32 v[8:9], v[8:9], v[16:17]
	v_pk_mul_f32 v[10:11], v[10:11], v[18:19]
	global_store_dwordx4 v[24:25], v[8:11], off offset:-3072
	s_load_dwordx2 s[12:13], s[0:1], 0x140
	s_waitcnt lgkmcnt(0)
	v_lshl_add_u64 v[8:9], s[12:13], 0, v[168:169]
	v_add_co_u32_e32 v8, vcc, s3, v8
	s_nop 1
	v_addc_co_u32_e32 v9, vcc, 0, v9, vcc
	s_nop 1
	v_mov_b64_e32 v[8:9], v[92:93]
	v_mov_b64_e32 v[10:11], v[94:95]
	v_pk_mul_f32 v[8:9], v[12:13], v[8:9]
	v_pk_mul_f32 v[10:11], v[14:15], v[10:11]
	global_store_dwordx4 v[24:25], v[8:11], off offset:-2048
	s_load_dwordx2 s[12:13], s[0:1], 0x140
	s_waitcnt lgkmcnt(0)
	v_lshl_add_u64 v[8:9], s[12:13], 0, v[168:169]
	v_add_co_u32_e32 v8, vcc, s3, v8
	s_nop 1
	v_addc_co_u32_e32 v9, vcc, 0, v9, vcc
	s_nop 1
	v_mov_b64_e32 v[8:9], v[96:97]
	v_mov_b64_e32 v[10:11], v[98:99]
	v_pk_mul_f32 v[4:5], v[4:5], v[8:9]
	v_pk_mul_f32 v[6:7], v[6:7], v[10:11]
	global_store_dwordx4 v[24:25], v[4:7], off offset:-1024
	s_load_dwordx2 s[12:13], s[0:1], 0x140
	s_waitcnt lgkmcnt(0)
	v_lshl_add_u64 v[4:5], s[12:13], 0, v[168:169]
	v_add_co_u32_e32 v4, vcc, s3, v4
	s_nop 1
	v_addc_co_u32_e32 v5, vcc, 0, v5, vcc
	s_nop 1
	v_mov_b64_e32 v[4:5], v[100:101]
	v_mov_b64_e32 v[6:7], v[102:103]
	v_cmp_lt_i32_e32 vcc, s74, v20
	s_or_b64 s[10:11], vcc, s[10:11]
	v_pk_mul_f32 v[0:1], v[0:1], v[4:5]
	v_pk_mul_f32 v[2:3], v[2:3], v[6:7]
	global_store_dwordx4 v[24:25], v[0:3], off
	s_andn2_b64 exec, exec, s[10:11]
	s_cbranch_execnz .LBB0_910
	s_getpc_b64 s[98:99]
